# GU phases: workgroups that own one tile fewer (wg >= nwg mod 256) start half a tile period later, shifting their epilogue bursts off the others'
# baseline (speedup 1.0000x reference)
.LBB0_732:
	s_or_b64 exec, exec, s[0:1]
	s_waitcnt lgkmcnt(0)
	v_mov_b32_e32 v0, v131
	v_readlane_b32 s0, v252, 63
	s_barrier
	v_readlane_b32 s1, v253, 0
	v_ashrrev_i32_e32 v1, 6, v0
	s_andn2_b64 vcc, exec, s[0:1]
	v_readfirstlane_b32 s0, v1
	s_cbranch_vccnz .LBB0_744
	v_readlane_b32 s94, v251, 0
	s_nop 1
	s_cmp_lt_u32 s94, 0xb0
	s_cbranch_scc1 .Lgu1_nostag
	s_sleep 112
	s_sleep 112
	s_sleep 112
	s_sleep 112
.Lgu1_nostag:
	v_lshlrev_b32_e32 v2, 4, v0
	v_add_u32_e32 v3, 0x2000, v2
	v_ashrrev_i32_e32 v4, 31, v3
	v_lshrrev_b32_e32 v4, 22, v4
	v_add_u32_e32 v4, v3, v4
	v_ashrrev_i32_e32 v4, 10, v4
	v_mul_i32_i24_e32 v6, 0x400, v4
	v_sub_u32_e32 v3, v3, v6
	v_lshrrev_b32_e32 v6, 4, v3
	v_bitop3_b32 v3, v6, v3, 32 bitop3:0x6c
	v_ashrrev_i32_e32 v6, 31, v3
	v_bfe_i32 v9, v0, 27, 1
	v_lshrrev_b32_e32 v6, 26, v6
	v_lshrrev_b32_e32 v9, 22, v9
	v_add_u32_e32 v6, v3, v6
	v_add_u32_e32 v9, v2, v9
	v_ashrrev_i32_e32 v7, 6, v6
	v_and_b32_e32 v6, 0xc0, v6
	v_and_b32_e32 v9, 0xfffffc00, v9
	v_sub_u32_e32 v3, v3, v6
	v_sub_u32_e32 v2, v2, v9
	v_lshlrev_b32_e32 v5, 5, v4
	v_ashrrev_i16_sdwa v3, v182, sext(v3) dst_sel:DWORD dst_unused:UNUSED_PAD src0_sel:DWORD src1_sel:BYTE_0
	v_lshlrev_b32_e32 v6, 3, v4
	v_lshrrev_b32_e32 v9, 4, v2
	v_and_b32_e32 v5, 32, v5
	v_bfe_i32 v3, v3, 0, 16
	v_and_b32_e32 v6, 0x1ffff0, v6
	v_bitop3_b32 v2, v9, v2, 32 bitop3:0x6c
	v_add_u32_e32 v5, v5, v3
	v_add_lshl_u32 v6, v7, v6, 11
	v_ashrrev_i32_e32 v9, 31, v2
	v_lshl_add_u32 v134, v5, 1, v6
	v_ashrrev_i32_e32 v5, 31, v0
	v_lshrrev_b32_e32 v9, 26, v9
	v_lshrrev_b32_e32 v5, 26, v5
	v_add_u32_e32 v9, v2, v9
	v_add_u32_e32 v5, v0, v5
	v_ashrrev_i32_e32 v10, 6, v9
	v_and_b32_e32 v9, 0xc0, v9
	v_ashrrev_i32_e32 v6, 6, v5
	v_sub_u32_e32 v2, v2, v9
	s_lshl_b32 s18, s0, 10
	v_lshlrev_b32_e32 v8, 5, v6
	v_ashrrev_i16_sdwa v2, v182, sext(v2) dst_sel:DWORD dst_unused:UNUSED_PAD src0_sel:DWORD src1_sel:BYTE_0
	v_lshlrev_b32_e32 v9, 3, v6
	v_and_b32_e32 v8, 32, v8
	v_bfe_i32 v2, v2, 0, 16
	v_and_b32_e32 v9, 0x1ffff0, v9
	s_add_i32 s19, s18, 32
	v_add_u32_e32 v8, v8, v2
	v_add_lshl_u32 v9, v10, v9, 11
	s_add_i32 s20, s19, 0x10000
	v_readlane_b32 s4, v253, 35
	v_lshl_add_u32 v128, v8, 1, v9
	s_waitcnt vmcnt(0)
	s_mov_b32 m0, s20
	v_readlane_b32 s5, v253, 36
	s_add_i32 s21, s19, 0x12000
	s_waitcnt lgkmcnt(0)
	s_barrier
	s_nop 2
	global_load_lds_dwordx4 v128, s[4:5]
	s_mov_b32 m0, s21
	v_readlane_b32 s6, v253, 39
	global_load_lds_dwordx4 v134, s[4:5]
	s_mov_b32 m0, s19
	v_readlane_b32 s7, v253, 40
	s_add_i32 s22, s19, 0x2000
	s_add_i32 s23, s19, 0x14000
	v_readlane_b32 s0, v253, 37
	v_readlane_b32 s1, v253, 38
	s_add_i32 s24, s19, 0x16000
	global_load_lds_dwordx4 v128, s[6:7]
	s_mov_b32 m0, s22
	s_add_i32 s25, s19, 0x4000
	global_load_lds_dwordx4 v134, s[6:7]
	s_mov_b32 m0, s23
	s_add_i32 s26, s19, 0x6000
	global_load_lds_dwordx4 v128, s[0:1]
	s_mov_b32 m0, s24
	v_ashrrev_i32_e32 v8, 8, v0
	global_load_lds_dwordx4 v134, s[0:1]
	v_readlane_b32 s0, v253, 41
	s_mov_b32 m0, s25
	v_readlane_b32 s1, v253, 42
	v_and_b32_e32 v9, 15, v0
	v_lshlrev_b32_e32 v1, 5, v1
	v_lshl_or_b32 v133, v8, 6, v9
	v_and_b32_e32 v150, 0x60, v1
	v_bfe_u32 v1, v0, 4, 2
	global_load_lds_dwordx4 v128, s[0:1]
	s_mov_b32 m0, s26
	v_lshlrev_b32_e32 v9, 6, v9
	global_load_lds_dwordx4 v134, s[0:1]
	s_movk_i32 s2, 0x100
	v_lshl_or_b32 v9, v1, 4, v9
	v_lshlrev_b32_e32 v11, 2, v0
	v_cmp_gt_u32_e64 s[2:3], s2, v0
	v_lshlrev_b32_e32 v0, 3, v1
	v_mov_b32_e32 v1, v129
	v_lshl_add_u64 v[136:137], s[80:81], 0, v[0:1]
	v_lshlrev_b32_e32 v0, 14, v4
	v_and_b32_e32 v0, 0xffff8000, v0
	v_lshl_add_u32 v0, v7, 11, v0
	v_lshlrev_b32_e32 v1, 6, v4
	v_and_or_b32 v0, v1, 64, v0
	v_lshl_add_u32 v138, v3, 1, v0
	v_lshlrev_b32_e32 v0, 14, v6
	v_and_b32_e32 v11, 32, v11
	v_lshlrev_b32_e32 v12, 7, v150
	v_and_b32_e32 v0, 0xffff8000, v0
	v_readlane_b32 s12, v253, 33
	v_bitop3_b32 v151, v9, v12, v11 bitop3:0xde
	v_lshlrev_b32_e32 v12, 13, v8
	v_lshl_add_u32 v0, v10, 11, v0
	v_readlane_b32 s13, v253, 34
	v_bitop3_b32 v9, v9, v12, v11 bitop3:0xde
	v_and_or_b32 v0, v5, 64, v0
	s_mov_b32 s28, s12
	v_readlane_b32 s12, v253, 31
	v_mov_b32_e32 v135, v129
	v_cmp_eq_u32_e64 s[0:1], 1, v8
	v_mov_b32_e32 v139, v129
	v_lshl_add_u32 v140, v2, 1, v0
	v_mov_b32_e32 v141, v129
	v_add_u32_e32 v152, 32, v9
	s_mov_b32 s29, s12
	v_readlane_b32 s27, v251, 0
	v_readlane_b32 s13, v253, 32
	s_branch .LBB0_735

.LBB0_1959:
	s_or_b64 exec, exec, s[0:1]
	s_waitcnt lgkmcnt(0)
	v_mov_b32_e32 v0, v131
	s_lshr_b32 s20, s22, 8
	s_barrier
	s_mul_i32 s21, s20, 22
	v_ashrrev_i32_e32 v1, 6, v0
	v_readlane_b32 s0, v251, 0
	s_cmp_ge_i32 s0, s21
	v_readfirstlane_b32 s0, v1
	s_cbranch_scc1 .LBB0_1971
	v_readlane_b32 s94, v251, 0
	s_and_b32 s95, s21, 0xff
	s_cmp_eq_u32 s95, 0
	s_cbranch_scc1 .Lgu2_nostag
	s_cmp_lt_u32 s94, s95
	s_cbranch_scc1 .Lgu2_nostag
	s_sleep 112
	s_sleep 112
	s_sleep 112
	s_sleep 112
.Lgu2_nostag:
	v_ashrrev_i32_e32 v2, 8, v0
	v_and_b32_e32 v3, 15, v0
	v_lshlrev_b32_e32 v1, 5, v1
	v_lshl_or_b32 v133, v2, 6, v3
	v_and_b32_e32 v150, 0x60, v1
	v_bfe_u32 v1, v0, 4, 2
	v_lshlrev_b32_e32 v3, 6, v3
	v_lshlrev_b32_e32 v4, 2, v0
	v_lshl_or_b32 v3, v1, 4, v3
	v_and_b32_e32 v4, 32, v4
	v_lshlrev_b32_e32 v5, 7, v150
	v_bitop3_b32 v151, v3, v5, v4 bitop3:0xde
	v_lshlrev_b32_e32 v5, 13, v2
	v_bitop3_b32 v3, v3, v5, v4 bitop3:0xde
	v_lshlrev_b32_e32 v4, 4, v0
	v_add_u32_e32 v5, 0x2000, v4
	v_ashrrev_i32_e32 v6, 31, v5
	v_lshrrev_b32_e32 v6, 22, v6
	v_add_u32_e32 v6, v5, v6
	v_ashrrev_i32_e32 v6, 10, v6
	v_mul_i32_i24_e32 v8, 0x400, v6
	v_sub_u32_e32 v5, v5, v8
	v_lshrrev_b32_e32 v8, 4, v5
	v_bitop3_b32 v5, v8, v5, 32 bitop3:0x6c
	v_ashrrev_i32_e32 v8, 31, v5
	v_bfe_i32 v11, v0, 27, 1
	v_lshrrev_b32_e32 v8, 26, v8
	v_lshrrev_b32_e32 v11, 22, v11
	s_lshl_b32 s22, s0, 10
	v_add_u32_e32 v8, v5, v8
	v_add_u32_e32 v11, v4, v11
	s_lshr_b32 s23, s21, 3
	v_readlane_b32 s0, v253, 7
	v_ashrrev_i32_e32 v9, 6, v8
	v_and_b32_e32 v8, 0xc0, v8
	v_and_b32_e32 v11, 0xfffffc00, v11
	s_or_b32 s24, s23, 1
	v_readlane_b32 s1, v253, 8
	v_sub_u32_e32 v5, v5, v8
	v_sub_u32_e32 v4, v4, v11
	s_and_b64 s[0:1], s[0:1], exec
	v_lshlrev_b32_e32 v7, 5, v6
	v_ashrrev_i16_sdwa v5, v182, sext(v5) dst_sel:DWORD dst_unused:UNUSED_PAD src0_sel:DWORD src1_sel:BYTE_0
	v_lshlrev_b32_e32 v8, 3, v6
	v_lshrrev_b32_e32 v11, 4, v4
	s_cselect_b32 s0, s24, s23
	v_readlane_b32 s1, v253, 23
	v_and_b32_e32 v7, 32, v7
	v_bfe_i32 v5, v5, 0, 16
	v_and_b32_e32 v8, 0x1ffff0, v8
	v_bitop3_b32 v4, v11, v4, 32 bitop3:0x6c
	s_mul_i32 s0, s0, s1
	v_readlane_b32 s1, v253, 43
	v_add_u32_e32 v7, v7, v5
	v_add_lshl_u32 v8, v9, v8, 11
	v_ashrrev_i32_e32 v11, 31, v4
	s_add_i32 s0, s0, s1
	v_lshl_add_u32 v134, v7, 1, v8
	v_ashrrev_i32_e32 v7, 31, v0
	v_lshrrev_b32_e32 v11, 26, v11
	s_mul_hi_i32 s1, s0, 0x2e8ba2e9
	v_lshrrev_b32_e32 v7, 26, v7
	v_add_u32_e32 v11, v4, v11
	s_lshr_b32 s4, s1, 31
	s_ashr_i32 s1, s1, 5
	v_add_u32_e32 v7, v0, v7
	v_ashrrev_i32_e32 v12, 6, v11
	v_and_b32_e32 v11, 0xc0, v11
	s_add_i32 s1, s1, s4
	v_ashrrev_i32_e32 v8, 6, v7
	v_sub_u32_e32 v4, v4, v11
	s_lshl_b32 s4, s1, 3
	v_lshlrev_b32_e32 v10, 5, v8
	v_ashrrev_i16_sdwa v4, v182, sext(v4) dst_sel:DWORD dst_unused:UNUSED_PAD src0_sel:DWORD src1_sel:BYTE_0
	v_lshlrev_b32_e32 v11, 3, v8
	s_sub_i32 s5, s20, s4
	v_and_b32_e32 v10, 32, v10
	v_bfe_i32 v4, v4, 0, 16
	v_and_b32_e32 v11, 0x1ffff0, v11
	s_min_i32 s5, s5, 8
	s_mulk_i32 s1, 0xb0
	v_add_u32_e32 v10, v10, v4
	v_add_lshl_u32 v11, v12, v11, 11
	s_sub_i32 s6, s0, s1
	s_sext_i32_i16 s0, s5
	v_lshl_add_u32 v128, v10, 1, v11
	v_cvt_f32_i32_e32 v11, s0
	v_cvt_f32_i32_e32 v10, s6
	s_xor_b32 s1, s6, s0
	s_ashr_i32 s1, s1, 30
	v_rcp_iflag_f32_e32 v13, v11
	s_or_b32 s7, s1, 1
	v_readlane_b32 s48, v251, 19
	v_readlane_b32 s56, v251, 27
	v_mul_f32_e32 v13, v10, v13
	v_trunc_f32_e32 v13, v13
	v_fma_f32 v10, -v13, v11, v10
	v_cvt_i32_f32_e32 v13, v13
	v_cmp_ge_f32_e64 s[0:1], |v10|, |v11|
	s_and_b64 s[0:1], s[0:1], exec
	s_cselect_b32 s0, s7, 0
	v_readfirstlane_b32 s1, v13
	s_add_i32 s0, s1, s0
	s_sext_i32_i16 s1, s0
	s_mul_i32 s0, s0, s5
	s_sub_i32 s0, s6, s0
	s_sext_i32_i16 s0, s0
	s_add_i32 s4, s4, s0
	s_lshl_b32 s16, s4, 8
	s_lshl_b32 s18, s1, 8
	s_ashr_i32 s17, s16, 31
	s_ashr_i32 s19, s18, 31
	s_lshl_b64 s[4:5], s[16:17], 11
	s_lshl_b64 s[0:1], s[18:19], 11
	v_readlane_b32 s6, v252, 43
	v_readlane_b32 s7, v252, 44
	s_add_u32 s0, s6, s0
	v_readlane_b32 s57, v251, 28
	s_addc_u32 s1, s7, s1
	s_add_i32 s17, s22, 32
	v_readlane_b32 s58, v251, 29
	v_readlane_b32 s59, v251, 30
	v_readlane_b32 s60, v251, 31
	v_readlane_b32 s61, v251, 32
	v_readlane_b32 s62, v251, 33
	v_readlane_b32 s63, v251, 34
	s_mov_b64 s[8:9], s[56:57]
	s_add_i32 s19, s17, 0x10000
	s_add_i32 s25, s17, 0x12000
	s_mov_b64 s[12:13], s[60:61]
	s_waitcnt vmcnt(0)
	s_mov_b32 m0, s19
	s_add_u32 s8, s12, s4
	s_waitcnt lgkmcnt(0)
	s_barrier
	global_load_lds_dwordx4 v128, s[0:1]
	s_mov_b32 m0, s25
	s_addc_u32 s9, s13, s5
	s_add_i32 s26, s17, 0x2000
	global_load_lds_dwordx4 v134, s[0:1]
	s_mov_b32 m0, s17
	s_add_u32 s4, s0, 0x40000
	global_load_lds_dwordx4 v128, s[8:9]
	s_mov_b32 m0, s26
	s_addc_u32 s5, s1, 0
	s_add_i32 s27, s17, 0x14000
	global_load_lds_dwordx4 v134, s[8:9]
	s_mov_b32 m0, s27
	s_add_i32 s28, s17, 0x16000
	global_load_lds_dwordx4 v128, s[4:5]
	s_mov_b32 m0, s28
	s_movk_i32 s6, 0x100
	global_load_lds_dwordx4 v134, s[4:5]
	s_add_u32 s4, s8, 0x40000
	s_addc_u32 s5, s9, 0
	s_add_i32 s29, s17, 0x4000
	s_mov_b32 m0, s29
	s_add_i32 s30, s17, 0x6000
	global_load_lds_dwordx4 v128, s[4:5]
	s_mov_b32 m0, s30
	v_cmp_gt_u32_e64 s[6:7], s6, v0
	global_load_lds_dwordx4 v134, s[4:5]
	v_lshlrev_b32_e32 v0, 3, v1
	v_mov_b32_e32 v1, v129
	v_lshl_add_u64 v[136:137], s[80:81], 0, v[0:1]
	v_lshlrev_b32_e32 v0, 14, v6
	v_and_b32_e32 v0, 0xffff8000, v0
	v_lshl_add_u32 v0, v9, 11, v0
	v_lshlrev_b32_e32 v1, 6, v6
	v_and_or_b32 v0, v1, 64, v0
	v_lshl_add_u32 v138, v5, 1, v0
	v_lshlrev_b32_e32 v0, 14, v8
	v_and_b32_e32 v0, 0xffff8000, v0
	v_lshl_add_u32 v0, v12, 11, v0
	v_and_or_b32 v0, v7, 64, v0
	v_mov_b32_e32 v135, v129
	v_cmp_eq_u32_e64 s[4:5], 1, v2
	v_mov_b32_e32 v139, v129
	v_lshl_add_u32 v140, v4, 1, v0
	v_mov_b32_e32 v141, v129
	v_add_u32_e32 v152, 32, v3
	v_readlane_b32 s31, v251, 0
	v_readlane_b32 s49, v251, 20
	v_readlane_b32 s50, v251, 21
	v_readlane_b32 s51, v251, 22
	v_readlane_b32 s52, v251, 23
	v_readlane_b32 s53, v251, 24
	v_readlane_b32 s54, v251, 25
	v_readlane_b32 s55, v251, 26
	s_mov_b64 s[10:11], s[58:59]
	s_mov_b64 s[14:15], s[62:63]
	s_waitcnt vmcnt(0)
	s_branch .LBB0_1962
